# attention global tiles (first unit's two loop copies): QK MFMAs read the prefetched K registers directly, eight 64-bit copies per global tile removed
# speedup vs baseline: 1.0044x; 1.0044x over previous
; __device__ __forceinline__ int next_tile(int tt, int R0) { while (tt < 26 && !tile_valid(tt, R0)) ++tt; return tt; }
; __device__ __forceinline__ void run_desc(int tt, int g, int c, int R0, int& cg, int& Rg) {
;     if (tt < 4) { cg = c; Rg = R0 - 16 + 4 * tt + g; }
;     else if (tt < 7) { cg = (c + 4 * (tt - 3)) & 15; Rg = R0 - 4 + g; }
;     else if (tt < 10) { const int o = 4 * (tt - 7) + g; const int o3 = (o * 11) >> 5; cg = (c + 1 + o3 * 4 + (o - 3 * o3)) & 15; Rg = R0 - 1; }
;     else { cg = tt - 10; Rg = R0 + g; }
; __device__ __forceinline__ void attn_task(const AttnP& P, LAS unsigned char* lds, int b, int hd, int qq, int c, float shift, int lane_in) {
;     ...
;         if (gi < 10 && (ph >= 2 || li >= 26)) {
;             attn_load_v(P, lds, hb, gi, c, R0, lane, vf);
; #pragma unroll
;             for (int kk = 0; kk < 4; ++kk) kf[kk] = gk[kk];
;             if (gi < 4) {
;                 if (gi == 0) { w0 = mT0[0]; w1 = mT0[1]; } else if (gi == 3) { w0 = mT3[0]; w1 = mT3[1]; } else { w0 = 0x0101010101010101ull; w1 = 0x0101010101010101ull; }
;             } else if (gi < 7) {
;                 const bool pos = c > ((c + 4 * (gi - 3)) & 15);
;                 w0 = pos ? mAp[0] : mAn[0]; w1 = pos ? mAp[1] : mAn[1];
;             } else {
;                 { int cg, Rg; run_desc(gi, h, c, R0, cg, Rg); w0 = (c > cg) ? mLp : mLn; }
;                 { int cg, Rg; run_desc(gi, 2 + h, c, R0, cg, Rg); w1 = (c > cg) ? mLp : mLn; }
;             }
;             gi = next_tile(gi + 1, R0);
;             if (gi < 10) attn_load_k(P, lds, hb, gi, c, R0, lane, gk);
.LBB0_203:
	s_add_i32 s0, s25, 4
	s_max_i32 s0, s0, s17
	s_not_b32 s1, s25
	s_add_i32 s0, s0, s1
	s_max_i32 s1, s23, 3
	s_lshr_b32 s0, s0, 2
	s_sub_i32 s1, s1, s23
	s_min_u32 s0, s0, s1
	s_add_i32 s0, s23, s0
	s_add_i32 s23, s0, 1
	s_waitcnt vmcnt(4)
	v_mfma_f32_32x32x16_bf16 v[66:81], v[110:113], v[86:89], 0
	v_mfma_f32_32x32x16_bf16 v[66:81], v[126:129], v[90:93], v[66:81]
	v_mfma_f32_32x32x16_bf16 v[66:81], v[130:133], v[94:97], v[66:81]
	v_mfma_f32_32x32x16_bf16 v[66:81], v[106:109], v[98:101], v[66:81]
	s_cmp_gt_i32 s0, 8
	s_cbranch_scc1 .Lattn_nopf_1
	s_lshl_b32 s4, s23, 2
	s_cmp_gt_i32 s0, 2
	s_mov_b64 s[0:1], -1
	s_cbranch_scc0 .LBB0_210
	s_cmp_gt_u32 s23, 6
	s_cbranch_scc0 .LBB0_207
	v_add_u32_e32 v246, s4, v230
	v_mul_u32_u24_e32 v247, 11, v246
	v_lshrrev_b32_e32 v247, 5, v247
	v_add3_u32 v246, v246, s62, v247
	v_and_b32_e32 v246, 15, v246
	s_mov_b64 s[0:1], 0
.LBB0_207:
	s_andn2_b64 vcc, exec, s[0:1]
	v_mov_b32_e32 v247, s15
	s_cbranch_vccnz .LBB0_209
	s_add_i32 s0, s4, s63
	s_and_b32 s0, s0, 15
	v_mov_b32_e32 v246, s0
	v_mov_b32_e32 v247, v231

; #define LAS __attribute__((address_space(3)))
; __device__ __forceinline__ void run_desc(int tt, int g, int c, int R0, int& cg, int& Rg) {
;     if (tt < 4) { cg = c; Rg = R0 - 16 + 4 * tt + g; }
;     else if (tt < 7) { cg = (c + 4 * (tt - 3)) & 15; Rg = R0 - 4 + g; }
;     else if (tt < 10) { const int o = 4 * (tt - 7) + g; const int o3 = (o * 11) >> 5; cg = (c + 1 + o3 * 4 + (o - 3 * o3)) & 15; Rg = R0 - 1; }
;     else { cg = tt - 10; Rg = R0 + g; }
; }
; __device__ __forceinline__ bool tile_valid(int tt, int R0) {
;     if (tt < 4) return R0 - 16 + 4 * tt >= 0;
;     if (tt < 7) return R0 >= 4;
;     if (tt < 10) return R0 >= 1;
;     return true;
; }
; __device__ __forceinline__ int next_tile(int tt, int R0) { while (tt < 26 && !tile_valid(tt, R0)) ++tt; return tt; }
; __device__ __forceinline__ void attn_load_k(const AttnP& P, LAS unsigned char* lds, int hb, int tt, int c, int R0, int lane, bf16x8 (&kf)[4]) {
;     const int rho = lane & 31, h = lane >> 5;
;     const int gk_ = 2 * (rho >> 4) + ((rho >> 2) & 1), pk_ = 4 * ((rho >> 3) & 1) + (rho & 3);
;     if (tt < 10) {
;         int cg, Rg; run_desc(tt, gk_, c, R0, cg, Rg);
;         const bf16_t* kp = P.K + ((size_t)(hb * 16 + cg) * 128 + 8 * Rg + pk_) * 64 + 8 * h;
; #pragma unroll
;         for (int kk = 0; kk < 4; ++kk) kf[kk] = *(const bf16x8*)(kp + 16 * kk);
.LBB0_210:
	s_andn2_b64 vcc, exec, s[0:1]
	s_cbranch_vccnz .LBB0_212
	v_add_u32_e32 v247, s4, v232
	v_mov_b32_e32 v246, s92
.LBB0_212:
	v_add_u32_e32 v190, s99, v246
	v_lshlrev_b32_e32 v246, 3, v247
	v_lshlrev_b64 v[248:249], 7, v[190:191]
	v_ashrrev_i32_e32 v247, 31, v246
	v_lshl_add_u64 v[246:247], v[248:249], 0, v[246:247]
	v_or_b32_e32 v246, v246, v198
	v_lshlrev_b64 v[246:247], 7, v[246:247]
	v_lshl_add_u64 v[246:247], v[206:207], 0, v[246:247]
	global_load_dwordx4 v[110:113], v[246:247], off
	global_load_dwordx4 v[126:129], v[246:247], off offset:32
	global_load_dwordx4 v[130:133], v[246:247], off offset:64
	global_load_dwordx4 v[106:109], v[246:247], off offset:96
	s_branch .Lattn_join_1

; __device__ __forceinline__ int next_tile(int tt, int R0) { while (tt < 26 && !tile_valid(tt, R0)) ++tt; return tt; }
; __device__ __forceinline__ void tile_compute(const bf16x8 (&kf)[4], const bf16x8 (&vf)[2][2], const bf16x8 (&qf)[4], unsigned long long w0, unsigned long long w1,
;                                              float shift, f32x16& o0, f32x16& o1, f32x16& zacc, const bf16x8& ones) {
;     ...
;     if (__builtin_amdgcn_readfirstlane(__builtin_bit_cast(int, shift)) != 0) {
; __device__ __forceinline__ void attn_task(const AttnP& P, LAS unsigned char* lds, int b, int hd, int qq, int c, float shift, int lane_in) {
;     ...
;             gi = next_tile(gi + 1, R0);
;             if (gi < 10) attn_load_k(P, lds, hb, gi, c, R0, lane, gk);
;             ph = 0;
.Lattn_join_1:
.LBB0_213:
	s_mov_b32 s10, 0
	s_and_b64 vcc, exec, s[100:101]
	s_cbranch_vccnz .LBB0_170
	s_branch .Lattn_sub_1

; __device__ __forceinline__ void tile_compute(const bf16x8 (&kf)[4], const bf16x8 (&vf)[2][2], const bf16x8 (&qf)[4], unsigned long long w0, unsigned long long w1,
;                                              float shift, f32x16& o0, f32x16& o1, f32x16& zacc, const bf16x8& ones) {
;     ...
;     if (__builtin_amdgcn_readfirstlane(__builtin_bit_cast(int, shift)) != 0) {
;         asm volatile("" ::: "memory");
; #pragma unroll
;         for (int e = 0; e < 16; ++e) st[e] -= shift;
;     }
.Lattn_sub_1:
	s_nop 10
	v_sub_f32_e32 v81, v81, v15
	v_sub_f32_e32 v80, v80, v16
	v_sub_f32_e32 v79, v79, v13
	v_sub_f32_e32 v78, v78, v14
	v_sub_f32_e32 v77, v77, v11
	v_sub_f32_e32 v76, v76, v12
	v_sub_f32_e32 v75, v75, v9
	v_sub_f32_e32 v74, v74, v10
	v_sub_f32_e32 v73, v73, v7
	v_sub_f32_e32 v72, v72, v8
	v_sub_f32_e32 v71, v71, v5
	v_sub_f32_e32 v70, v70, v6
	v_sub_f32_e32 v69, v69, v3
	v_sub_f32_e32 v68, v68, v4
	v_sub_f32_e32 v67, v67, v1
	v_sub_f32_e32 v66, v66, v2
	s_branch .LBB0_170

; #define LAS __attribute__((address_space(3)))
; __device__ __forceinline__ void run_desc(int tt, int g, int c, int R0, int& cg, int& Rg) {
;     if (tt < 4) { cg = c; Rg = R0 - 16 + 4 * tt + g; }
;     else if (tt < 7) { cg = (c + 4 * (tt - 3)) & 15; Rg = R0 - 4 + g; }
;     else if (tt < 10) { const int o = 4 * (tt - 7) + g; const int o3 = (o * 11) >> 5; cg = (c + 1 + o3 * 4 + (o - 3 * o3)) & 15; Rg = R0 - 1; }
;     else { cg = tt - 10; Rg = R0 + g; }
; }
; __device__ __forceinline__ bool tile_valid(int tt, int R0) {
;     if (tt < 4) return R0 - 16 + 4 * tt >= 0;
;     if (tt < 7) return R0 >= 4;
;     if (tt < 10) return R0 >= 1;
;     return true;
; }
; __device__ __forceinline__ int next_tile(int tt, int R0) { while (tt < 26 && !tile_valid(tt, R0)) ++tt; return tt; }
; __device__ __forceinline__ void attn_load_k(const AttnP& P, LAS unsigned char* lds, int hb, int tt, int c, int R0, int lane, bf16x8 (&kf)[4]) {
;     const int rho = lane & 31, h = lane >> 5;
;     const int gk_ = 2 * (rho >> 4) + ((rho >> 2) & 1), pk_ = 4 * ((rho >> 3) & 1) + (rho & 3);
;     if (tt < 10) {
;         int cg, Rg; run_desc(tt, gk_, c, R0, cg, Rg);
;         const bf16_t* kp = P.K + ((size_t)(hb * 16 + cg) * 128 + 8 * Rg + pk_) * 64 + 8 * h;
; #pragma unroll
;         for (int kk = 0; kk < 4; ++kk) kf[kk] = *(const bf16x8*)(kp + 16 * kk);
; __device__ __forceinline__ void tile_compute(const bf16x8 (&kf)[4], const bf16x8 (&vf)[2][2], const bf16x8 (&qf)[4], unsigned long long w0, unsigned long long w1,
;                                              float shift, f32x16& o0, f32x16& o1, f32x16& zacc, const bf16x8& ones) {
;     ...
;     for (int kk = 0; kk < 4; ++kk) st = __builtin_amdgcn_mfma_f32_32x32x16_bf16(kf[kk], qf[kk], st, 0, 0, 0);
.LBB0_283:
	s_add_i32 s0, s21, 4
	s_max_i32 s0, s0, s17
	s_not_b32 s1, s21
	s_add_i32 s0, s0, s1
	s_max_i32 s1, s14, 3
	s_lshr_b32 s0, s0, 2
	s_sub_i32 s1, s1, s14
	s_min_u32 s0, s0, s1
	s_add_i32 s0, s14, s0
	s_add_i32 s14, s0, 1
	s_waitcnt vmcnt(4)
	v_mfma_f32_32x32x16_bf16 v[66:81], v[110:113], v[86:89], 0
	v_mfma_f32_32x32x16_bf16 v[66:81], v[126:129], v[90:93], v[66:81]
	v_mfma_f32_32x32x16_bf16 v[66:81], v[130:133], v[94:97], v[66:81]
	v_mfma_f32_32x32x16_bf16 v[66:81], v[106:109], v[98:101], v[66:81]
	s_cmp_gt_i32 s0, 8
	s_cbranch_scc1 .Lattn_nopf_2
	s_lshl_b32 s4, s14, 2
	s_cmp_gt_i32 s0, 2
	s_mov_b64 s[0:1], -1
	s_cbranch_scc0 .LBB0_290
	s_cmp_gt_u32 s14, 6
	s_cbranch_scc0 .LBB0_287
	v_add_u32_e32 v246, s4, v17
	v_mul_u32_u24_e32 v247, 11, v246
	v_lshrrev_b32_e32 v247, 5, v247
	v_add3_u32 v246, v246, s65, v247
	v_and_b32_e32 v246, 15, v246
	s_mov_b64 s[0:1], 0
.LBB0_287:
	s_andn2_b64 vcc, exec, s[0:1]
	v_mov_b32_e32 v247, s15
	s_cbranch_vccnz .LBB0_289
	s_add_i32 s0, s4, s70
	s_and_b32 s0, s0, 15
	v_mov_b32_e32 v246, s0
	v_mov_b32_e32 v247, v231

; __device__ __forceinline__ void run_desc(int tt, int g, int c, int R0, int& cg, int& Rg) {
;     if (tt < 4) { cg = c; Rg = R0 - 16 + 4 * tt + g; }
;     else if (tt < 7) { cg = (c + 4 * (tt - 3)) & 15; Rg = R0 - 4 + g; }
;     else if (tt < 10) { const int o = 4 * (tt - 7) + g; const int o3 = (o * 11) >> 5; cg = (c + 1 + o3 * 4 + (o - 3 * o3)) & 15; Rg = R0 - 1; }
;     else { cg = tt - 10; Rg = R0 + g; }
.LBB0_290:
	s_andn2_b64 vcc, exec, s[0:1]
	s_cbranch_vccnz .LBB0_292
	v_add_u32_e32 v247, s4, v232
	v_mov_b32_e32 v246, s64
